# stack4 + remaining sigmoid divisions -> v_rcp (packed op_sel reads parsed), dead DPP old-value inits removed in the FFN epilogue
# speedup vs baseline: 1.0062x; 1.0062x over previous
;     __device__ __forceinline__ void operator()(const f32x4 (&acc)[2][2][4][2], const Unit& u, int wr, int wc, int fr, int fq) const {
;     ...
;         tile_rs(SS, u.pm, rsl);
;         f32x4 gs[2][4][2];
; _Pragma("unroll")
;         for (int ai = 0; ai < 2; ++ai)
; _Pragma("unroll")
;             for (int m = 0; m < 4; ++m) { const float rs = rsl[128 * ai + 64 * wr + 16 * m + fr]; gs[ai][m][0] = acc[ai][0][m][0] * rs; gs[ai][m][1] = acc[ai][0][m][1] * rs; }
;         if (fr >= 14) {
;             const bool seq_end = (u.pm & 15) == 15;
; _Pragma("unroll")
;             for (int ai = 0; ai < 2; ++ai) { const int q = 2 * ai + wr + 1; const int slot = q < 4 ? q : 4 + ((u.pm + 1) & 1); const bool zero = (q == 4) && seq_end;
; _Pragma("unroll")
;                 for (int n = 0; n < 2; ++n) *(LAS f32x4*)(hal + halo_idx(slot, wc, fr - 14, ci0 + 4 * n)) = zero ? (f32x4){0.f, 0.f, 0.f, 0.f} : gs[ai][3][n];
;                 if (seq_end && ai == 1 && wr == 1) {
;                     float* co = out + O_CP + (size_t)((u.pm >> 4) * 2 + (fr - 14)) * FF + ch0; *(f32x4*)co = gs[1][3][0]; *(f32x4*)(co + 4) = gs[1][3][1]; } }
;         }
;         asm volatile("s_waitcnt lgkmcnt(0)" ::: "memory"); __builtin_amdgcn_s_barrier(); asm volatile("" ::: "memory");
;         f32x4 w0[2], w1[2], w2[2], bb[2];
; _Pragma("unroll")
;         for (int n = 0; n < 2; ++n) { w0[n] = *(const f32x4*)(cw_ + ch0 + 4 * n); w1[n] = *(const f32x4*)(cw_ + FF + ch0 + 4 * n); w2[n] = *(const f32x4*)(cw_ + 2 * FF + ch0 + 4 * n); bb[n] = *(const f32x4*)(cb_ + ch0 + 4 * n); }
; _Pragma("unroll")
;         for (int ai = 0; ai < 2; ++ai)
; _Pragma("unroll")
;             for (int m = 0; m < 4; ++m) { const int r = row0 + 128 * ai + 16 * m; const float rs = rsl[128 * ai + 64 * wr + 16 * m + fr]; f32x4 o[2];
; _Pragma("unroll")
;                 for (int n = 0; n < 2; ++n) { f32x4 p1, p2, q1, q2;
;                     if (m > 0) {
; _Pragma("unroll")
;                         for (int j = 0; j < 4; ++j) { q1[j] = row_from_below<1>(gs[ai][m - 1][n][j]); q2[j] = row_from_below<2>(gs[ai][m - 1][n][j]); } }
;                     else { const int slot = (2 * ai + wr) ? (2 * ai + wr) : 4 + (u.pm & 1);
;                         q1 = *(const LAS f32x4*)(hal + halo_idx(slot, wc, 1, ci0 + 4 * n)); q2 = *(const LAS f32x4*)(hal + halo_idx(slot, wc, fr == 0 ? 0 : 1, ci0 + 4 * n)); }
; _Pragma("unroll")
.LBB0_1086:
	s_or_b64 exec, exec, s[0:1]
	s_waitcnt lgkmcnt(0)
	s_barrier
	s_waitcnt vmcnt(0)
	v_mov_b32_e32 v58, v220
	v_mov_b32_e32 v59, v221
	v_mov_b32_e32 v60, v222
	v_mov_b32_e32 v61, v223
	v_mov_b32_e32 v70, v224
	v_mov_b32_e32 v71, v225
	v_mov_b32_e32 v72, v226
	v_mov_b32_e32 v73, v227
	v_mov_b32_e32 v62, v232
	v_mov_b32_e32 v63, v233
	v_mov_b32_e32 v64, v234
	v_mov_b32_e32 v65, v235
	v_mov_b32_e32 v66, v236
	v_mov_b32_e32 v67, v237
	v_mov_b32_e32 v68, v238
	v_mov_b32_e32 v69, v239
	v_pk_mul_f32 v[166:167], v[44:45], v[172:173] op_sel_hi:[1,0]
	v_pk_mul_f32 v[168:169], v[42:43], v[172:173] op_sel_hi:[1,0]
	v_pk_mul_f32 v[170:171], v[48:49], v[172:173] op_sel_hi:[1,0]
	v_pk_mul_f32 v[172:173], v[46:47], v[172:173] op_sel_hi:[1,0]
	v_mov_b32_e32 v218, v185
	v_pk_mul_f32 v[174:175], v[52:53], v[184:185] op_sel_hi:[1,0]
	v_pk_mul_f32 v[176:177], v[50:51], v[184:185] op_sel_hi:[1,0]
	v_pk_mul_f32 v[182:183], v[56:57], v[184:185] op_sel_hi:[1,0]
	v_pk_mul_f32 v[184:185], v[54:55], v[184:185] op_sel_hi:[1,0]
	v_mov_b32_e32 v42, v240
	v_mov_b32_e32 v43, v241
	v_mov_b32_e32 v44, v242
	v_mov_b32_e32 v45, v243
	v_mov_b32_e32 v46, v244
	v_mov_b32_e32 v47, v245
	v_mov_b32_e32 v48, v246
	v_mov_b32_e32 v49, v247
	v_mov_b32_e32 v50, v248
	v_mov_b32_e32 v51, v249
	v_mov_b32_e32 v52, v250
	v_mov_b32_e32 v53, v251
	global_load_dwordx4 v[54:57], v[164:165], off offset:16
	v_pk_mul_f32 v[190:191], v[122:123], v[194:195] op_sel_hi:[1,0]
	v_pk_mul_f32 v[230:231], v[134:135], v[192:193] op_sel_hi:[1,0]
	v_or_b32_e32 v123, 4, v195
	v_mov_b32_e32 v134, s64
	v_cndmask_b32_e64 v123, v134, v123, s[12:13]
	v_lshl_or_b32 v123, v123, 3, s72
	v_pk_mul_f32 v[132:133], v[132:133], v[192:193] op_sel_hi:[1,0]
	v_pk_mul_f32 v[226:227], v[130:131], v[192:193] op_sel_hi:[1,0]
	v_pk_mul_f32 v[228:229], v[136:137], v[192:193] op_sel_hi:[1,0]
	v_or_b32_e32 v192, v123, v203
	v_pk_mul_f32 v[124:125], v[124:125], v[194:195] op_sel_hi:[1,0]
	v_pk_mul_f32 v[128:129], v[128:129], v[194:195] op_sel_hi:[1,0]
	v_pk_mul_f32 v[126:127], v[126:127], v[194:195] op_sel_hi:[1,0]
	v_mov_b32_e32 v194, v193
	v_lshl_add_u32 v123, v123, 7, v204
	v_lshl_add_u32 v222, v192, 7, v204
	v_pk_mul_f32 v[108:109], v[108:109], v[218:219] op_sel_hi:[1,0]
	v_pk_mul_f32 v[106:107], v[106:107], v[218:219] op_sel_hi:[1,0]
	v_pk_mul_f32 v[112:113], v[112:113], v[218:219] op_sel_hi:[1,0]
	v_pk_mul_f32 v[110:111], v[110:111], v[218:219] op_sel_hi:[1,0]
	v_pk_mul_f32 v[116:117], v[116:117], v[194:195] op_sel_hi:[1,0]
	v_pk_mul_f32 v[114:115], v[114:115], v[194:195] op_sel_hi:[1,0]
	v_pk_mul_f32 v[120:121], v[120:121], v[194:195] op_sel_hi:[1,0]
	v_pk_mul_f32 v[130:131], v[118:119], v[194:195] op_sel_hi:[1,0]
	ds_read2_b32 v[118:119], v214 offset1:16
	ds_read_b128 v[134:137], v123 offset:128
	ds_read_b128 v[192:195], v123 offset:144
	ds_read_b128 v[218:221], v222
	ds_read_b128 v[222:225], v222 offset:16
	v_mov_b32_dpp v233, v230 row_ror:2 row_mask:0xf bank_mask:0xf
	v_mov_b32_dpp v235, v231 row_ror:2 row_mask:0xf bank_mask:0xf
	v_mov_b32_dpp v232, v230 row_ror:1 row_mask:0xf bank_mask:0xf
	v_mov_b32_dpp v234, v231 row_ror:1 row_mask:0xf bank_mask:0xf
	s_waitcnt lgkmcnt(0)
	v_cndmask_b32_e64 v219, v219, v235, s[10:11]
	v_cndmask_b32_e64 v218, v218, v233, s[10:11]
	v_cndmask_b32_e64 v135, v234, v135, s[8:9]
	v_cndmask_b32_e64 v134, v232, v134, s[8:9]
	v_mov_b32_dpp v237, v228 row_ror:2 row_mask:0xf bank_mask:0xf
	v_mov_b32_dpp v239, v229 row_ror:2 row_mask:0xf bank_mask:0xf
	v_mov_b32_dpp v236, v228 row_ror:1 row_mask:0xf bank_mask:0xf
	v_mov_b32_dpp v238, v229 row_ror:1 row_mask:0xf bank_mask:0xf
	v_cndmask_b32_e64 v221, v221, v239, s[10:11]
	v_cndmask_b32_e64 v220, v220, v237, s[10:11]
	v_cndmask_b32_e64 v137, v238, v137, s[8:9]
	v_cndmask_b32_e64 v136, v236, v136, s[8:9]
	v_pk_mul_f32 v[102:103], v[102:103], v[118:119] op_sel_hi:[1,0]
	v_pk_mul_f32 v[104:105], v[104:105], v[118:119] op_sel_hi:[1,0]
	v_pk_mul_f32 v[98:99], v[98:99], v[118:119] op_sel_hi:[1,0]
	v_add_u32_e32 v122, s30, v212
	v_pk_mul_f32 v[100:101], v[100:101], v[118:119] op_sel_hi:[1,0]
	s_cmp_eq_u32 s78, s75
	s_waitcnt vmcnt(0)
	v_pk_fma_f32 v[218:219], v[58:59], v[218:219], v[70:71]
	s_nop 0
	v_pk_fma_f32 v[134:135], v[62:63], v[134:135], v[218:219]
	v_pk_fma_f32 v[220:221], v[60:61], v[220:221], v[72:73]
	v_pk_fma_f32 v[134:135], v[230:231], v[66:67], v[134:135]
	v_pk_fma_f32 v[136:137], v[64:65], v[136:137], v[220:221]
	v_mul_f32_e32 v123, 0xbfb8aa3b, v134
	v_mul_f32_e32 v219, 0xbfb8aa3b, v135
	v_exp_f32_e32 v218, v123
	v_exp_f32_e32 v219, v219
	v_pk_fma_f32 v[136:137], v[228:229], v[68:69], v[136:137]
	v_mov_b32_dpp v118, v130 row_ror:1 row_mask:0xf bank_mask:0xf
	v_pk_add_f32 v[218:219], v[218:219], 1.0 op_sel_hi:[1,0]
	s_nop 0
	v_rcp_f32_e32 v219, v219
	v_mul_f32_e32 v220, 0xbfb8aa3b, v136
	v_mul_f32_e32 v221, 0xbfb8aa3b, v137
	v_exp_f32_e32 v220, v220
	v_exp_f32_e32 v221, v221
	v_rcp_f32_e32 v218, v218
	s_nop 0
	v_pk_mul_f32 v[134:135], v[134:135], v[218:219]
	v_pk_add_f32 v[220:221], v[220:221], 1.0 op_sel_hi:[1,0]
	v_pk_mul_f32 v[102:103], v[102:103], v[134:135]
	v_rcp_f32_e32 v135, v221
	v_rcp_f32_e32 v134, v220
	v_mov_b32_dpp v218, v226 row_ror:1 row_mask:0xf bank_mask:0xf
	v_mov_b32_dpp v219, v226 row_ror:2 row_mask:0xf bank_mask:0xf
	v_mov_b32_dpp v220, v227 row_ror:1 row_mask:0xf bank_mask:0xf
	v_mov_b32_dpp v221, v227 row_ror:2 row_mask:0xf bank_mask:0xf
	v_pk_mul_f32 v[134:135], v[136:137], v[134:135]
	v_cndmask_b32_e64 v137, v220, v193, s[8:9]
	v_cndmask_b32_e64 v136, v218, v192, s[8:9]
	v_cndmask_b32_e64 v193, v223, v221, s[10:11]
	v_cndmask_b32_e64 v192, v222, v219, s[10:11]
	v_pk_fma_f32 v[192:193], v[42:43], v[192:193], v[54:55]
; #define LAS __attribute__((address_space(3)))
; __device__ __forceinline__ size_t hidx(size_t r, int c) { return ((size_t)(c >> 6) * MTOT + r) * 64 + (c & 63); }
; __device__ __forceinline__ u32x4 pack8(const f32x4 a, const f32x4 b) { u32x4 w; w.x = cvt_pk_bf16(a[0], a[1]); w.y = cvt_pk_bf16(a[2], a[3]); w.z = cvt_pk_bf16(b[0], b[1]); w.w = cvt_pk_bf16(b[2], b[3]); return w; }
; __device__ __forceinline__ float sigm(float x) { return 1.f / (1.f + __builtin_amdgcn_exp2f(-LOG2E * x)); }
; __device__ __forceinline__ int halo_idx(int slot, int wc, int row, int ci) { return ((slot * 4 + wc) * 2 + row) * 32 + ci; }
;     __device__ __forceinline__ void operator()(const f32x4 (&acc)[2][2][4][2], const Unit& u, int wr, int wc, int fr, int fq) const {
;     ...
;             for (int m = 0; m < 4; ++m) { const int r = row0 + 128 * ai + 16 * m; const float rs = rsl[128 * ai + 64 * wr + 16 * m + fr]; f32x4 o[2];
; _Pragma("unroll")
;                 for (int n = 0; n < 2; ++n) { f32x4 p1, p2, q1, q2;
;                     if (m > 0) {
; _Pragma("unroll")
;                         for (int j = 0; j < 4; ++j) { q1[j] = row_from_below<1>(gs[ai][m - 1][n][j]); q2[j] = row_from_below<2>(gs[ai][m - 1][n][j]); } }
;                     else { const int slot = (2 * ai + wr) ? (2 * ai + wr) : 4 + (u.pm & 1);
;                         q1 = *(const LAS f32x4*)(hal + halo_idx(slot, wc, 1, ci0 + 4 * n)); q2 = *(const LAS f32x4*)(hal + halo_idx(slot, wc, fr == 0 ? 0 : 1, ci0 + 4 * n)); }
; _Pragma("unroll")
;                     for (int j = 0; j < 4; ++j) { p1[j] = row_from_below<1>(gs[ai][m][n][j]); p2[j] = row_from_below<2>(gs[ai][m][n][j]); }
;                     const f32x4 h1 = fr >= 1 ? p1 : q1, h0 = fr >= 2 ? p2 : q2;
;                     const f32x4 cv = bb[n] + w0[n] * h0 + w1[n] * h1 + w2[n] * gs[ai][m][n];
; _Pragma("unroll")
;                     for (int j = 0; j < 4; ++j) o[n][j] = cv[j] * sigm(cv[j]) * (acc[ai][1][m][n][j] * rs); }
;                 *(u32x4*)(H + hidx(r, ch0)) = pack8(o[0], o[1]); }
	v_mov_b32_dpp v228, v132 row_ror:1 row_mask:0xf bank_mask:0xf
	v_pk_fma_f32 v[136:137], v[46:47], v[136:137], v[192:193]
	v_mov_b32_dpp v229, v132 row_ror:2 row_mask:0xf bank_mask:0xf
	v_pk_fma_f32 v[136:137], v[226:227], v[50:51], v[136:137]
	v_mov_b32_dpp v230, v133 row_ror:1 row_mask:0xf bank_mask:0xf
	v_mul_f32_e32 v123, 0xbfb8aa3b, v136
	v_exp_f32_e32 v192, v123
	v_mul_f32_e32 v123, 0xbfb8aa3b, v137
	v_exp_f32_e32 v193, v123
	v_mov_b32_dpp v231, v133 row_ror:2 row_mask:0xf bank_mask:0xf
	v_pk_mul_f32 v[104:105], v[104:105], v[134:135]
	v_cndmask_b32_e64 v135, v230, v195, s[8:9]
	v_pk_add_f32 v[192:193], v[192:193], 1.0 op_sel_hi:[1,0]
	v_cndmask_b32_e64 v134, v228, v194, s[8:9]
	v_cndmask_b32_e64 v195, v225, v231, s[10:11]
	v_cndmask_b32_e64 v194, v224, v229, s[10:11]
	v_pk_fma_f32 v[194:195], v[44:45], v[194:195], v[56:57]
	s_nop 0
	v_pk_fma_f32 v[134:135], v[48:49], v[134:135], v[194:195]
	s_nop 0
	v_pk_fma_f32 v[132:133], v[132:133], v[52:53], v[134:135]
	v_rcp_f32_e32 v135, v193
	v_mul_f32_e32 v134, 0xbfb8aa3b, v132
	v_exp_f32_e32 v194, v134
	v_mul_f32_e32 v134, 0xbfb8aa3b, v133
	v_exp_f32_e32 v195, v134
	v_rcp_f32_e32 v134, v192
	s_nop 0
	v_pk_mul_f32 v[134:135], v[136:137], v[134:135]
	v_pk_add_f32 v[192:193], v[194:195], 1.0 op_sel_hi:[1,0]
	v_pk_mul_f32 v[134:135], v[98:99], v[134:135]
	s_nop 0
	v_rcp_f32_e32 v99, v193
	v_rcp_f32_e32 v98, v192
	s_nop 0
	v_pk_mul_f32 v[98:99], v[132:133], v[98:99]
	v_ashrrev_i32_e32 v123, 31, v122
	v_pk_mul_f32 v[132:133], v[100:101], v[98:99]
	v_cvt_pk_bf16_f32 v98, v102, v103
	v_lshl_add_u64 v[102:103], s[48:49], 0, v[122:123]
	v_cvt_pk_bf16_f32 v101, v132, v133
	v_lshlrev_b64 v[102:103], 7, v[102:103]
	v_cvt_pk_bf16_f32 v99, v104, v105
	v_cvt_pk_bf16_f32 v100, v134, v135
	v_lshl_add_u64 v[102:103], v[156:157], 0, v[102:103]
	v_mov_b32_dpp v123, v130 row_ror:2 row_mask:0xf bank_mask:0xf
	v_mov_b32_dpp v133, v131 row_ror:2 row_mask:0xf bank_mask:0xf
	global_store_dwordx4 v[102:103], v[98:101], off
	v_mov_b32_dpp v132, v131 row_ror:1 row_mask:0xf bank_mask:0xf
	v_cndmask_b32_e64 v103, v235, v133, s[10:11]
	v_cndmask_b32_e64 v102, v233, v123, s[10:11]
	v_cndmask_b32_e64 v101, v132, v234, s[8:9]
	v_cndmask_b32_e64 v100, v118, v232, s[8:9]
	v_pk_fma_f32 v[102:103], v[58:59], v[102:103], v[70:71]
	s_nop 0
	v_pk_fma_f32 v[100:101], v[62:63], v[100:101], v[102:103]
	s_nop 0
	v_pk_fma_f32 v[100:101], v[130:131], v[66:67], v[100:101]
	s_nop 0
	v_mul_f32_e32 v98, 0xbfb8aa3b, v100
	v_exp_f32_e32 v102, v98
	v_mul_f32_e32 v98, 0xbfb8aa3b, v101
	v_exp_f32_e32 v103, v98
	v_mov_b32_dpp v135, v120 row_ror:2 row_mask:0xf bank_mask:0xf
	v_mov_b32_dpp v137, v121 row_ror:2 row_mask:0xf bank_mask:0xf
	v_pk_add_f32 v[102:103], v[102:103], 1.0 op_sel_hi:[1,0]
	v_mov_b32_dpp v134, v120 row_ror:1 row_mask:0xf bank_mask:0xf
	v_mov_b32_dpp v136, v121 row_ror:1 row_mask:0xf bank_mask:0xf
	v_cndmask_b32_e64 v105, v239, v137, s[10:11]
	v_cndmask_b32_e64 v104, v237, v135, s[10:11]
	v_cndmask_b32_e64 v99, v136, v238, s[8:9]
	v_cndmask_b32_e64 v98, v134, v236, s[8:9]
	v_pk_fma_f32 v[104:105], v[60:61], v[104:105], v[72:73]
	s_nop 0
	v_pk_fma_f32 v[98:99], v[64:65], v[98:99], v[104:105]
	s_nop 0
	v_pk_fma_f32 v[98:99], v[120:121], v[68:69], v[98:99]
	v_rcp_f32_e32 v103, v103
	v_mul_f32_e32 v104, 0xbfb8aa3b, v98
	v_mul_f32_e32 v105, 0xbfb8aa3b, v99
	v_exp_f32_e32 v104, v104
	v_exp_f32_e32 v105, v105
	v_rcp_f32_e32 v102, v102
	s_nop 0
	v_pk_mul_f32 v[100:101], v[100:101], v[102:103]
	v_pk_add_f32 v[102:103], v[104:105], 1.0 op_sel_hi:[1,0]
	v_mov_b32_e32 v104, v119
	v_pk_mul_f32 v[94:95], v[94:95], v[104:105] op_sel_hi:[1,0]
	s_nop 0
	v_pk_mul_f32 v[94:95], v[94:95], v[100:101]
	v_rcp_f32_e32 v101, v103
	v_pk_mul_f32 v[96:97], v[96:97], v[104:105] op_sel_hi:[1,0]
	v_mov_b32_dpp v119, v114 row_ror:2 row_mask:0xf bank_mask:0xf
	v_mov_b32_dpp v121, v115 row_ror:2 row_mask:0xf bank_mask:0xf
	v_rcp_f32_e32 v100, v102
	v_mov_b32_dpp v105, v114 row_ror:1 row_mask:0xf bank_mask:0xf
	v_mov_b32_dpp v120, v115 row_ror:1 row_mask:0xf bank_mask:0xf
	v_cndmask_b32_e64 v103, v221, v121, s[10:11]
	v_cndmask_b32_e64 v102, v219, v119, s[10:11]
	v_pk_mul_f32 v[98:99], v[98:99], v[100:101]
	v_cndmask_b32_e64 v101, v120, v220, s[8:9]
	v_cndmask_b32_e64 v100, v105, v218, s[8:9]
	v_pk_fma_f32 v[102:103], v[42:43], v[102:103], v[54:55]
	v_pk_mul_f32 v[96:97], v[96:97], v[98:99]
	v_pk_fma_f32 v[100:101], v[46:47], v[100:101], v[102:103]
	s_nop 0
	v_pk_fma_f32 v[100:101], v[114:115], v[50:51], v[100:101]
	s_nop 0
	v_mul_f32_e32 v98, 0xbfb8aa3b, v100
	v_exp_f32_e32 v102, v98
	v_mul_f32_e32 v98, 0xbfb8aa3b, v101
	v_exp_f32_e32 v103, v98
	v_mov_b32_dpp v131, v116 row_ror:2 row_mask:0xf bank_mask:0xf
	v_mov_b32_dpp v193, v117 row_ror:2 row_mask:0xf bank_mask:0xf
	v_pk_add_f32 v[102:103], v[102:103], 1.0 op_sel_hi:[1,0]
	v_mov_b32_dpp v130, v116 row_ror:1 row_mask:0xf bank_mask:0xf
	v_mov_b32_dpp v192, v117 row_ror:1 row_mask:0xf bank_mask:0xf
	v_cndmask_b32_e64 v115, v231, v193, s[10:11]
	v_cndmask_b32_e64 v114, v229, v131, s[10:11]
	v_cndmask_b32_e64 v99, v192, v230, s[8:9]
	v_cndmask_b32_e64 v98, v130, v228, s[8:9]
	v_pk_fma_f32 v[114:115], v[44:45], v[114:115], v[56:57]
	v_pk_mul_f32 v[90:91], v[90:91], v[104:105] op_sel_hi:[1,0]
	v_pk_fma_f32 v[98:99], v[48:49], v[98:99], v[114:115]
	s_nop 0
	v_pk_fma_f32 v[98:99], v[116:117], v[52:53], v[98:99]
	v_rcp_f32_e32 v103, v103
	v_mul_f32_e32 v114, 0xbfb8aa3b, v98
	v_mul_f32_e32 v115, 0xbfb8aa3b, v99
	v_exp_f32_e32 v114, v114
	v_exp_f32_e32 v115, v115
	v_rcp_f32_e32 v102, v102
	s_nop 0
	v_pk_mul_f32 v[100:101], v[100:101], v[102:103]
	v_pk_add_f32 v[114:115], v[114:115], 1.0 op_sel_hi:[1,0]
; #define LAS __attribute__((address_space(3)))
; __device__ __forceinline__ size_t hidx(size_t r, int c) { return ((size_t)(c >> 6) * MTOT + r) * 64 + (c & 63); }
; __device__ __forceinline__ u32x4 pack8(const f32x4 a, const f32x4 b) { u32x4 w; w.x = cvt_pk_bf16(a[0], a[1]); w.y = cvt_pk_bf16(a[2], a[3]); w.z = cvt_pk_bf16(b[0], b[1]); w.w = cvt_pk_bf16(b[2], b[3]); return w; }
; __device__ __forceinline__ float sigm(float x) { return 1.f / (1.f + __builtin_amdgcn_exp2f(-LOG2E * x)); }
; __device__ __forceinline__ int halo_idx(int slot, int wc, int row, int ci) { return ((slot * 4 + wc) * 2 + row) * 32 + ci; }
;     __device__ __forceinline__ void operator()(const f32x4 (&acc)[2][2][4][2], const Unit& u, int wr, int wc, int fr, int fq) const {
;     ...
;             for (int m = 0; m < 4; ++m) { const int r = row0 + 128 * ai + 16 * m; const float rs = rsl[128 * ai + 64 * wr + 16 * m + fr]; f32x4 o[2];
; _Pragma("unroll")
;                 for (int n = 0; n < 2; ++n) { f32x4 p1, p2, q1, q2;
;                     if (m > 0) {
; _Pragma("unroll")
;                         for (int j = 0; j < 4; ++j) { q1[j] = row_from_below<1>(gs[ai][m - 1][n][j]); q2[j] = row_from_below<2>(gs[ai][m - 1][n][j]); } }
;                     else { const int slot = (2 * ai + wr) ? (2 * ai + wr) : 4 + (u.pm & 1);
;                         q1 = *(const LAS f32x4*)(hal + halo_idx(slot, wc, 1, ci0 + 4 * n)); q2 = *(const LAS f32x4*)(hal + halo_idx(slot, wc, fr == 0 ? 0 : 1, ci0 + 4 * n)); }
; _Pragma("unroll")
;                     for (int j = 0; j < 4; ++j) { p1[j] = row_from_below<1>(gs[ai][m][n][j]); p2[j] = row_from_below<2>(gs[ai][m][n][j]); }
;                     const f32x4 h1 = fr >= 1 ? p1 : q1, h0 = fr >= 2 ? p2 : q2;
;                     const f32x4 cv = bb[n] + w0[n] * h0 + w1[n] * h1 + w2[n] * gs[ai][m][n];
; _Pragma("unroll")
;                     for (int j = 0; j < 4; ++j) o[n][j] = cv[j] * sigm(cv[j]) * (acc[ai][1][m][n][j] * rs); }
;                 *(u32x4*)(H + hidx(r, ch0)) = pack8(o[0], o[1]); }
	v_pk_mul_f32 v[100:101], v[90:91], v[100:101]
	v_pk_mul_f32 v[92:93], v[92:93], v[104:105] op_sel_hi:[1,0]
	v_rcp_f32_e32 v91, v115
	v_rcp_f32_e32 v90, v114
	v_or_b32_e32 v102, 16, v122
	v_pk_mul_f32 v[90:91], v[98:99], v[90:91]
	v_ashrrev_i32_e32 v103, 31, v102
	v_pk_mul_f32 v[98:99], v[92:93], v[90:91]
	v_cvt_pk_bf16_f32 v90, v94, v95
	v_cvt_pk_bf16_f32 v92, v100, v101
	v_lshl_add_u64 v[94:95], s[48:49], 0, v[102:103]
	v_lshlrev_b64 v[94:95], 7, v[94:95]
	v_mov_b32_dpp v101, v126 row_ror:2 row_mask:0xf bank_mask:0xf
	v_mov_b32_dpp v103, v127 row_ror:2 row_mask:0xf bank_mask:0xf
	v_cvt_pk_bf16_f32 v91, v96, v97
	v_cvt_pk_bf16_f32 v93, v98, v99
	v_lshl_add_u64 v[94:95], v[156:157], 0, v[94:95]
	v_mov_b32_dpp v100, v126 row_ror:1 row_mask:0xf bank_mask:0xf
	v_mov_b32_dpp v102, v127 row_ror:1 row_mask:0xf bank_mask:0xf
	v_cndmask_b32_e64 v97, v133, v103, s[10:11]
	v_cndmask_b32_e64 v96, v123, v101, s[10:11]
	global_store_dwordx4 v[94:95], v[90:93], off
	v_cndmask_b32_e64 v95, v102, v132, s[8:9]
	v_cndmask_b32_e64 v94, v100, v118, s[8:9]
	v_pk_fma_f32 v[96:97], v[58:59], v[96:97], v[70:71]
	s_nop 0
	v_pk_fma_f32 v[94:95], v[62:63], v[94:95], v[96:97]
	s_nop 0
	v_pk_fma_f32 v[94:95], v[126:127], v[66:67], v[94:95]
	v_mov_b32_dpp v114, v128 row_ror:2 row_mask:0xf bank_mask:0xf
	v_mul_f32_e32 v92, 0xbfb8aa3b, v94
	v_exp_f32_e32 v96, v92
	v_mul_f32_e32 v92, 0xbfb8aa3b, v95
	v_exp_f32_e32 v97, v92
	v_mov_b32_dpp v116, v129 row_ror:2 row_mask:0xf bank_mask:0xf
	v_mov_b32_dpp v104, v128 row_ror:1 row_mask:0xf bank_mask:0xf
	v_pk_add_f32 v[96:97], v[96:97], 1.0 op_sel_hi:[1,0]
	v_mov_b32_dpp v115, v129 row_ror:1 row_mask:0xf bank_mask:0xf
	v_cndmask_b32_e64 v99, v137, v116, s[10:11]
	v_cndmask_b32_e64 v98, v135, v114, s[10:11]
	v_cndmask_b32_e64 v93, v115, v136, s[8:9]
	v_cndmask_b32_e64 v92, v104, v134, s[8:9]
	v_pk_fma_f32 v[98:99], v[60:61], v[98:99], v[72:73]
	ds_read2_b32 v[90:91], v214 offset0:32 offset1:48
	v_pk_fma_f32 v[92:93], v[64:65], v[92:93], v[98:99]
	v_rcp_f32_e32 v97, v97
	v_pk_fma_f32 v[92:93], v[128:129], v[68:69], v[92:93]
	s_nop 0
	v_mul_f32_e32 v98, 0xbfb8aa3b, v92
	v_mul_f32_e32 v99, 0xbfb8aa3b, v93
	v_exp_f32_e32 v98, v98
	v_exp_f32_e32 v99, v99
	v_rcp_f32_e32 v96, v96
	s_nop 0
	v_pk_mul_f32 v[94:95], v[94:95], v[96:97]
	v_pk_add_f32 v[98:99], v[98:99], 1.0 op_sel_hi:[1,0]
	s_waitcnt lgkmcnt(0)
	v_pk_mul_f32 v[86:87], v[86:87], v[90:91] op_sel_hi:[1,0]
	s_nop 0
	v_pk_mul_f32 v[86:87], v[86:87], v[94:95]
	v_rcp_f32_e32 v95, v99
	v_mov_b32_dpp v118, v190 row_ror:2 row_mask:0xf bank_mask:0xf
	v_mov_b32_dpp v126, v191 row_ror:2 row_mask:0xf bank_mask:0xf
	v_rcp_f32_e32 v94, v98
	v_mov_b32_dpp v117, v190 row_ror:1 row_mask:0xf bank_mask:0xf
	v_mov_b32_dpp v123, v191 row_ror:1 row_mask:0xf bank_mask:0xf
	v_cndmask_b32_e64 v97, v121, v126, s[10:11]
	v_cndmask_b32_e64 v96, v119, v118, s[10:11]
	v_pk_mul_f32 v[92:93], v[92:93], v[94:95]
	v_cndmask_b32_e64 v95, v123, v120, s[8:9]
	v_cndmask_b32_e64 v94, v117, v105, s[8:9]
	v_pk_fma_f32 v[96:97], v[42:43], v[96:97], v[54:55]
	v_pk_mul_f32 v[88:89], v[88:89], v[90:91] op_sel_hi:[1,0]
	v_pk_fma_f32 v[94:95], v[46:47], v[94:95], v[96:97]
	v_pk_mul_f32 v[88:89], v[88:89], v[92:93]
	v_pk_fma_f32 v[94:95], v[190:191], v[50:51], v[94:95]
	s_nop 0
	v_mul_f32_e32 v92, 0xbfb8aa3b, v94
	v_exp_f32_e32 v96, v92
	v_mul_f32_e32 v92, 0xbfb8aa3b, v95
	v_exp_f32_e32 v97, v92
	v_mov_b32_dpp v128, v124 row_ror:2 row_mask:0xf bank_mask:0xf
	v_pk_add_f32 v[96:97], v[96:97], 1.0 op_sel_hi:[1,0]
	v_mov_b32_dpp v132, v125 row_ror:2 row_mask:0xf bank_mask:0xf
	v_mov_b32_dpp v127, v124 row_ror:1 row_mask:0xf bank_mask:0xf
	v_mov_b32_dpp v129, v125 row_ror:1 row_mask:0xf bank_mask:0xf
	v_cndmask_b32_e64 v99, v193, v132, s[10:11]
	v_cndmask_b32_e64 v98, v131, v128, s[10:11]
	v_cndmask_b32_e64 v93, v129, v192, s[8:9]
	v_cndmask_b32_e64 v92, v127, v130, s[8:9]
	v_pk_fma_f32 v[98:99], v[44:45], v[98:99], v[56:57]
	v_pk_mul_f32 v[82:83], v[82:83], v[90:91] op_sel_hi:[1,0]
	v_pk_fma_f32 v[92:93], v[48:49], v[92:93], v[98:99]
	v_rcp_f32_e32 v97, v97
	v_pk_fma_f32 v[92:93], v[124:125], v[52:53], v[92:93]
	s_nop 0
	v_mul_f32_e32 v98, 0xbfb8aa3b, v92
	v_mul_f32_e32 v99, 0xbfb8aa3b, v93
	v_exp_f32_e32 v98, v98
	v_exp_f32_e32 v99, v99
	v_rcp_f32_e32 v96, v96
	s_nop 0
	v_pk_mul_f32 v[94:95], v[94:95], v[96:97]
	v_pk_add_f32 v[98:99], v[98:99], 1.0 op_sel_hi:[1,0]
	v_pk_mul_f32 v[94:95], v[82:83], v[94:95]
	v_pk_mul_f32 v[84:85], v[84:85], v[90:91] op_sel_hi:[1,0]
	v_rcp_f32_e32 v83, v99
	v_rcp_f32_e32 v82, v98
	v_or_b32_e32 v96, 32, v122
	v_pk_mul_f32 v[82:83], v[92:93], v[82:83]
	v_ashrrev_i32_e32 v97, 31, v96
	v_pk_mul_f32 v[92:93], v[84:85], v[82:83]
	v_cvt_pk_bf16_f32 v82, v86, v87
	v_lshl_add_u64 v[86:87], s[48:49], 0, v[96:97]
	v_lshlrev_b64 v[86:87], 7, v[86:87]
	v_cvt_pk_bf16_f32 v83, v88, v89
	v_cvt_pk_bf16_f32 v84, v94, v95
	v_cvt_pk_bf16_f32 v85, v92, v93
	v_lshl_add_u64 v[86:87], v[156:157], 0, v[86:87]
	global_store_dwordx4 v[86:87], v[82:85], off
	s_nop 0
	v_mov_b32_dpp v86, v188 row_ror:2 row_mask:0xf bank_mask:0xf
	v_mov_b32_dpp v87, v189 row_ror:2 row_mask:0xf bank_mask:0xf
	v_mov_b32_dpp v82, v188 row_ror:1 row_mask:0xf bank_mask:0xf
	v_mov_b32_dpp v84, v189 row_ror:1 row_mask:0xf bank_mask:0xf
	v_cndmask_b32_e64 v87, v103, v87, s[10:11]
	v_cndmask_b32_e64 v86, v101, v86, s[10:11]
	v_cndmask_b32_e64 v85, v84, v102, s[8:9]
	v_cndmask_b32_e64 v84, v82, v100, s[8:9]
	v_pk_fma_f32 v[86:87], v[58:59], v[86:87], v[70:71]
	s_nop 0
	v_pk_fma_f32 v[84:85], v[62:63], v[84:85], v[86:87]
	v_mov_b32_dpp v90, v186 row_ror:2 row_mask:0xf bank_mask:0xf
	v_pk_fma_f32 v[84:85], v[188:189], v[66:67], v[84:85]
; #define LAS __attribute__((address_space(3)))
; __device__ __forceinline__ size_t hidx(size_t r, int c) { return ((size_t)(c >> 6) * MTOT + r) * 64 + (c & 63); }
; __device__ __forceinline__ u32x4 pack8(const f32x4 a, const f32x4 b) { u32x4 w; w.x = cvt_pk_bf16(a[0], a[1]); w.y = cvt_pk_bf16(a[2], a[3]); w.z = cvt_pk_bf16(b[0], b[1]); w.w = cvt_pk_bf16(b[2], b[3]); return w; }
; __device__ __forceinline__ int halo_idx(int slot, int wc, int row, int ci) { return ((slot * 4 + wc) * 2 + row) * 32 + ci; }
; __device__ __forceinline__ float sigm(float x) { return 1.f / (1.f + __builtin_amdgcn_exp2f(-LOG2E * x)); }
;     __device__ __forceinline__ void operator()(const f32x4 (&acc)[2][2][4][2], const Unit& u, int wr, int wc, int fr, int fq) const {
;     ...
;             for (int m = 0; m < 4; ++m) { const int r = row0 + 128 * ai + 16 * m; const float rs = rsl[128 * ai + 64 * wr + 16 * m + fr]; f32x4 o[2];
; _Pragma("unroll")
;                 for (int n = 0; n < 2; ++n) { f32x4 p1, p2, q1, q2;
;                     if (m > 0) {
; _Pragma("unroll")
;                         for (int j = 0; j < 4; ++j) { q1[j] = row_from_below<1>(gs[ai][m - 1][n][j]); q2[j] = row_from_below<2>(gs[ai][m - 1][n][j]); } }
;                     else { const int slot = (2 * ai + wr) ? (2 * ai + wr) : 4 + (u.pm & 1);
;                         q1 = *(const LAS f32x4*)(hal + halo_idx(slot, wc, 1, ci0 + 4 * n)); q2 = *(const LAS f32x4*)(hal + halo_idx(slot, wc, fr == 0 ? 0 : 1, ci0 + 4 * n)); }
; _Pragma("unroll")
;                     for (int j = 0; j < 4; ++j) { p1[j] = row_from_below<1>(gs[ai][m][n][j]); p2[j] = row_from_below<2>(gs[ai][m][n][j]); }
;                     const f32x4 h1 = fr >= 1 ? p1 : q1, h0 = fr >= 2 ? p2 : q2;
;                     const f32x4 cv = bb[n] + w0[n] * h0 + w1[n] * h1 + w2[n] * gs[ai][m][n];
; _Pragma("unroll")
;                     for (int j = 0; j < 4; ++j) o[n][j] = cv[j] * sigm(cv[j]) * (acc[ai][1][m][n][j] * rs); }
;                 *(u32x4*)(H + hidx(r, ch0)) = pack8(o[0], o[1]); }
	v_mov_b32_dpp v88, v186 row_ror:1 row_mask:0xf bank_mask:0xf
	v_mul_f32_e32 v82, 0xbfb8aa3b, v84
	v_exp_f32_e32 v86, v82
	v_mul_f32_e32 v82, 0xbfb8aa3b, v85
	v_exp_f32_e32 v87, v82
	v_cndmask_b32_e64 v82, v88, v104, s[8:9]
	v_cndmask_b32_e64 v88, v114, v90, s[10:11]
	v_pk_add_f32 v[86:87], v[86:87], 1.0 op_sel_hi:[1,0]
	v_mov_b32_dpp v89, v187 row_ror:2 row_mask:0xf bank_mask:0xf
	v_mov_b32_dpp v83, v187 row_ror:1 row_mask:0xf bank_mask:0xf
	v_cndmask_b32_e64 v89, v116, v89, s[10:11]
	v_cndmask_b32_e64 v83, v83, v115, s[8:9]
	v_pk_fma_f32 v[88:89], v[60:61], v[88:89], v[72:73]
	v_mov_b32_e32 v95, 0
	v_pk_fma_f32 v[82:83], v[64:65], v[82:83], v[88:89]
	v_rcp_f32_e32 v87, v87
	v_pk_fma_f32 v[82:83], v[186:187], v[68:69], v[82:83]
	s_nop 0
	v_mul_f32_e32 v88, 0xbfb8aa3b, v82
	v_mul_f32_e32 v89, 0xbfb8aa3b, v83
	v_exp_f32_e32 v88, v88
	v_exp_f32_e32 v89, v89
	v_rcp_f32_e32 v86, v86
	s_nop 0
	v_pk_mul_f32 v[84:85], v[84:85], v[86:87]
	v_pk_add_f32 v[86:87], v[88:89], 1.0 op_sel_hi:[1,0]
	v_mov_b32_e32 v88, v91
	v_pk_mul_f32 v[78:79], v[78:79], v[88:89] op_sel_hi:[1,0]
	v_mov_b32_e32 v97, 0
	v_pk_mul_f32 v[78:79], v[78:79], v[84:85]
	v_rcp_f32_e32 v85, v87
	v_pk_mul_f32 v[80:81], v[80:81], v[88:89] op_sel_hi:[1,0]
	v_rcp_f32_e32 v84, v86
	s_nop 0
	v_pk_mul_f32 v[82:83], v[82:83], v[84:85]
	s_nop 0
	v_pk_mul_f32 v[80:81], v[80:81], v[82:83]
	v_mov_b32_dpp v86, v180 row_ror:2 row_mask:0xf bank_mask:0xf
	v_mov_b32_dpp v87, v181 row_ror:2 row_mask:0xf bank_mask:0xf
	v_mov_b32_dpp v82, v180 row_ror:1 row_mask:0xf bank_mask:0xf
	v_mov_b32_dpp v84, v181 row_ror:1 row_mask:0xf bank_mask:0xf
	v_cndmask_b32_e64 v87, v126, v87, s[10:11]
	v_cndmask_b32_e64 v86, v118, v86, s[10:11]
	v_cndmask_b32_e64 v85, v84, v123, s[8:9]
	v_cndmask_b32_e64 v84, v82, v117, s[8:9]
	v_pk_fma_f32 v[86:87], v[42:43], v[86:87], v[54:55]
	s_nop 0
	v_pk_fma_f32 v[84:85], v[46:47], v[84:85], v[86:87]
	s_nop 0
	v_pk_fma_f32 v[84:85], v[180:181], v[50:51], v[84:85]
	v_mov_b32_dpp v89, v178 row_ror:1 row_mask:0xf bank_mask:0xf
	v_mul_f32_e32 v82, 0xbfb8aa3b, v84
	v_exp_f32_e32 v86, v82
	v_mul_f32_e32 v82, 0xbfb8aa3b, v85
	v_exp_f32_e32 v87, v82
	v_cndmask_b32_e64 v82, v89, v127, s[8:9]
	v_mov_b32_dpp v90, v178 row_ror:2 row_mask:0xf bank_mask:0xf
	v_pk_add_f32 v[86:87], v[86:87], 1.0 op_sel_hi:[1,0]
	v_mov_b32_dpp v91, v179 row_ror:2 row_mask:0xf bank_mask:0xf
	v_mov_b32_dpp v83, v179 row_ror:1 row_mask:0xf bank_mask:0xf
	v_cndmask_b32_e64 v91, v132, v91, s[10:11]
	v_cndmask_b32_e64 v90, v128, v90, s[10:11]
	v_cndmask_b32_e64 v83, v83, v129, s[8:9]
	v_pk_fma_f32 v[90:91], v[44:45], v[90:91], v[56:57]
	s_nop 0
	v_pk_fma_f32 v[82:83], v[48:49], v[82:83], v[90:91]
	v_rcp_f32_e32 v87, v87
	v_pk_fma_f32 v[82:83], v[178:179], v[52:53], v[82:83]
	s_nop 0
	v_mul_f32_e32 v90, 0xbfb8aa3b, v82
	v_mul_f32_e32 v91, 0xbfb8aa3b, v83
	v_exp_f32_e32 v90, v90
	v_exp_f32_e32 v91, v91
	v_rcp_f32_e32 v86, v86
	s_nop 0
	v_pk_mul_f32 v[84:85], v[84:85], v[86:87]
	v_pk_add_f32 v[90:91], v[90:91], 1.0 op_sel_hi:[1,0]
	v_mov_b32_dpp v95, v184 row_ror:2 row_mask:0xf bank_mask:0xf
	v_pk_mul_f32 v[74:75], v[74:75], v[88:89] op_sel_hi:[1,0]
	s_nop 0
	v_pk_mul_f32 v[84:85], v[74:75], v[84:85]
	v_rcp_f32_e32 v75, v91
	v_rcp_f32_e32 v74, v90
	v_or_b32_e32 v86, 48, v122
	v_pk_mul_f32 v[74:75], v[82:83], v[74:75]
	v_pk_mul_f32 v[76:77], v[76:77], v[88:89] op_sel_hi:[1,0]
	v_ashrrev_i32_e32 v87, 31, v86
	v_pk_mul_f32 v[82:83], v[76:77], v[74:75]
	v_cvt_pk_bf16_f32 v74, v78, v79
	v_lshl_add_u64 v[78:79], s[48:49], 0, v[86:87]
	v_lshlrev_b64 v[78:79], 7, v[78:79]
	v_cvt_pk_bf16_f32 v75, v80, v81
	v_cvt_pk_bf16_f32 v76, v84, v85
	v_cvt_pk_bf16_f32 v77, v82, v83
	v_lshl_add_u64 v[78:79], v[156:157], 0, v[78:79]
	global_store_dwordx4 v[78:79], v[74:77], off
	ds_read_b32 v84, v146
	v_mov_b32_dpp v97, v185 row_ror:2 row_mask:0xf bank_mask:0xf
	v_add_u32_e32 v74, s74, v204
	ds_read_b128 v[88:91], v74 offset:128
	ds_read_b128 v[74:77], v74 offset:144
	ds_read_b128 v[100:103], v217
	v_mov_b32_dpp v94, v184 row_ror:1 row_mask:0xf bank_mask:0xf
	v_mov_b32_dpp v96, v185 row_ror:1 row_mask:0xf bank_mask:0xf
	s_waitcnt lgkmcnt(2)
	v_cndmask_b32_e64 v89, v96, v89, s[8:9]
	s_waitcnt lgkmcnt(0)
	v_cndmask_b32_e64 v93, v101, v97, s[10:11]
	v_cndmask_b32_e64 v92, v100, v95, s[10:11]
	v_cndmask_b32_e64 v88, v94, v88, s[8:9]
	v_pk_fma_f32 v[92:93], v[58:59], v[92:93], v[70:71]
	s_nop 0
	v_pk_fma_f32 v[88:89], v[62:63], v[88:89], v[92:93]
	v_mov_b32_dpp v87, v182 row_ror:2 row_mask:0xf bank_mask:0xf
	v_pk_fma_f32 v[92:93], v[184:185], v[66:67], v[88:89]
	v_mov_b32_dpp v98, v183 row_ror:2 row_mask:0xf bank_mask:0xf
	v_mul_f32_e32 v83, 0xbfb8aa3b, v92
	v_exp_f32_e32 v88, v83
	v_mul_f32_e32 v83, 0xbfb8aa3b, v93
	v_exp_f32_e32 v89, v83
	v_cndmask_b32_e64 v101, v103, v98, s[10:11]
	v_cndmask_b32_e64 v100, v102, v87, s[10:11]
	v_pk_add_f32 v[102:103], v[88:89], 1.0 op_sel_hi:[1,0]
	v_mov_b32_dpp v85, v182 row_ror:1 row_mask:0xf bank_mask:0xf
	v_mov_b32_dpp v99, v183 row_ror:1 row_mask:0xf bank_mask:0xf
	v_cndmask_b32_e64 v91, v99, v91, s[8:9]
	v_cndmask_b32_e64 v90, v85, v90, s[8:9]
	v_pk_fma_f32 v[88:89], v[60:61], v[100:101], v[72:73]
	v_pk_mul_f32 v[30:31], v[30:31], v[84:85] op_sel_hi:[1,0]
	v_pk_fma_f32 v[88:89], v[64:65], v[90:91], v[88:89]
	v_rcp_f32_e32 v91, v103
	v_pk_fma_f32 v[88:89], v[182:183], v[68:69], v[88:89]
	s_nop 0
	v_mul_f32_e32 v90, 0xbfb8aa3b, v88
	v_exp_f32_e32 v100, v90
	v_mul_f32_e32 v90, 0xbfb8aa3b, v89
	v_exp_f32_e32 v101, v90
	v_rcp_f32_e32 v90, v102
	s_nop 0
	v_pk_mul_f32 v[92:93], v[92:93], v[90:91]
	v_pk_add_f32 v[90:91], v[100:101], 1.0 op_sel_hi:[1,0]
	v_pk_mul_f32 v[30:31], v[30:31], v[92:93]
	ds_read_b128 v[78:81], v217 offset:16
	ds_read_b32 v86, v214 offset:704
	v_pk_mul_f32 v[32:33], v[32:33], v[84:85] op_sel_hi:[1,0]
	v_rcp_f32_e32 v91, v91
	v_pk_mul_f32 v[26:27], v[26:27], v[84:85] op_sel_hi:[1,0]
	v_rcp_f32_e32 v90, v90
	s_nop 0
	v_pk_mul_f32 v[88:89], v[88:89], v[90:91]
	s_nop 0
	v_pk_mul_f32 v[32:33], v[32:33], v[88:89]
	s_nop 0
	v_mov_b32_dpp v89, v176 row_ror:2 row_mask:0xf bank_mask:0xf
	v_mov_b32_dpp v91, v177 row_ror:2 row_mask:0xf bank_mask:0xf
	v_mov_b32_dpp v88, v176 row_ror:1 row_mask:0xf bank_mask:0xf
	v_mov_b32_dpp v90, v177 row_ror:1 row_mask:0xf bank_mask:0xf
	s_waitcnt lgkmcnt(1)
; #define LAS __attribute__((address_space(3)))
; __device__ __forceinline__ size_t hidx(size_t r, int c) { return ((size_t)(c >> 6) * MTOT + r) * 64 + (c & 63); }
; __device__ __forceinline__ u32x4 pack8(const f32x4 a, const f32x4 b) { u32x4 w; w.x = cvt_pk_bf16(a[0], a[1]); w.y = cvt_pk_bf16(a[2], a[3]); w.z = cvt_pk_bf16(b[0], b[1]); w.w = cvt_pk_bf16(b[2], b[3]); return w; }
; __device__ __forceinline__ float sigm(float x) { return 1.f / (1.f + __builtin_amdgcn_exp2f(-LOG2E * x)); }
; __device__ __forceinline__ int halo_idx(int slot, int wc, int row, int ci) { return ((slot * 4 + wc) * 2 + row) * 32 + ci; }
;     __device__ __forceinline__ void operator()(const f32x4 (&acc)[2][2][4][2], const Unit& u, int wr, int wc, int fr, int fq) const {
;     ...
;             for (int m = 0; m < 4; ++m) { const int r = row0 + 128 * ai + 16 * m; const float rs = rsl[128 * ai + 64 * wr + 16 * m + fr]; f32x4 o[2];
; _Pragma("unroll")
;                 for (int n = 0; n < 2; ++n) { f32x4 p1, p2, q1, q2;
;                     if (m > 0) {
; _Pragma("unroll")
;                         for (int j = 0; j < 4; ++j) { q1[j] = row_from_below<1>(gs[ai][m - 1][n][j]); q2[j] = row_from_below<2>(gs[ai][m - 1][n][j]); } }
;                     else { const int slot = (2 * ai + wr) ? (2 * ai + wr) : 4 + (u.pm & 1);
;                         q1 = *(const LAS f32x4*)(hal + halo_idx(slot, wc, 1, ci0 + 4 * n)); q2 = *(const LAS f32x4*)(hal + halo_idx(slot, wc, fr == 0 ? 0 : 1, ci0 + 4 * n)); }
; _Pragma("unroll")
;                     for (int j = 0; j < 4; ++j) { p1[j] = row_from_below<1>(gs[ai][m][n][j]); p2[j] = row_from_below<2>(gs[ai][m][n][j]); }
;                     const f32x4 h1 = fr >= 1 ? p1 : q1, h0 = fr >= 2 ? p2 : q2;
;                     const f32x4 cv = bb[n] + w0[n] * h0 + w1[n] * h1 + w2[n] * gs[ai][m][n];
; _Pragma("unroll")
;                     for (int j = 0; j < 4; ++j) o[n][j] = cv[j] * sigm(cv[j]) * (acc[ai][1][m][n][j] * rs); }
;                 *(u32x4*)(H + hidx(r, ch0)) = pack8(o[0], o[1]); }
	v_cndmask_b32_e64 v79, v79, v91, s[10:11]
	v_cndmask_b32_e64 v78, v78, v89, s[10:11]
	v_cndmask_b32_e64 v75, v90, v75, s[8:9]
	v_cndmask_b32_e64 v74, v88, v74, s[8:9]
	v_pk_fma_f32 v[78:79], v[42:43], v[78:79], v[54:55]
	s_nop 0
	v_pk_fma_f32 v[74:75], v[46:47], v[74:75], v[78:79]
	s_nop 0
	v_pk_fma_f32 v[74:75], v[176:177], v[50:51], v[74:75]
	s_nop 0
	v_mul_f32_e32 v78, 0xbfb8aa3b, v74
	v_mul_f32_e32 v79, 0xbfb8aa3b, v75
	v_exp_f32_e32 v78, v78
	v_exp_f32_e32 v79, v79
	v_mov_b32_dpp v93, v174 row_ror:2 row_mask:0xf bank_mask:0xf
	v_mov_b32_dpp v101, v175 row_ror:2 row_mask:0xf bank_mask:0xf
	v_pk_add_f32 v[78:79], v[78:79], 1.0 op_sel_hi:[1,0]
	v_mov_b32_dpp v92, v174 row_ror:1 row_mask:0xf bank_mask:0xf
	v_mov_b32_dpp v100, v175 row_ror:1 row_mask:0xf bank_mask:0xf
	v_cndmask_b32_e64 v81, v81, v101, s[10:11]
	v_cndmask_b32_e64 v80, v80, v93, s[10:11]
	v_cndmask_b32_e64 v77, v100, v77, s[8:9]
	v_cndmask_b32_e64 v76, v92, v76, s[8:9]
	v_pk_fma_f32 v[80:81], v[44:45], v[80:81], v[56:57]
	v_add_u32_e32 v82, 0x80, v122
	v_pk_fma_f32 v[76:77], v[48:49], v[76:77], v[80:81]
	v_rcp_f32_e32 v79, v79
	v_pk_fma_f32 v[76:77], v[174:175], v[52:53], v[76:77]
	s_nop 0
	v_mul_f32_e32 v80, 0xbfb8aa3b, v76
	v_mul_f32_e32 v81, 0xbfb8aa3b, v77
	v_exp_f32_e32 v80, v80
	v_exp_f32_e32 v81, v81
	v_rcp_f32_e32 v78, v78
	s_nop 0
	v_pk_mul_f32 v[74:75], v[74:75], v[78:79]
	v_pk_add_f32 v[80:81], v[80:81], 1.0 op_sel_hi:[1,0]
	v_pk_mul_f32 v[74:75], v[26:27], v[74:75]
	v_pk_mul_f32 v[28:29], v[28:29], v[84:85] op_sel_hi:[1,0]
	v_rcp_f32_e32 v27, v81
	v_rcp_f32_e32 v26, v80
	s_nop 0
	v_pk_mul_f32 v[26:27], v[76:77], v[26:27]
	v_ashrrev_i32_e32 v83, 31, v82
	v_pk_mul_f32 v[76:77], v[28:29], v[26:27]
	v_cvt_pk_bf16_f32 v26, v30, v31
	v_cvt_pk_bf16_f32 v29, v76, v77
	v_lshl_add_u64 v[30:31], s[48:49], 0, v[82:83]
	v_lshlrev_b64 v[30:31], 7, v[30:31]
	v_mov_b32_dpp v77, v110 row_ror:2 row_mask:0xf bank_mask:0xf
	v_mov_b32_dpp v79, v111 row_ror:2 row_mask:0xf bank_mask:0xf
	v_cvt_pk_bf16_f32 v27, v32, v33
	v_cvt_pk_bf16_f32 v28, v74, v75
	v_lshl_add_u64 v[30:31], v[156:157], 0, v[30:31]
	v_mov_b32_dpp v76, v110 row_ror:1 row_mask:0xf bank_mask:0xf
	v_mov_b32_dpp v78, v111 row_ror:1 row_mask:0xf bank_mask:0xf
	v_cndmask_b32_e64 v33, v97, v79, s[10:11]
	v_cndmask_b32_e64 v32, v95, v77, s[10:11]
	global_store_dwordx4 v[30:31], v[26:29], off
	v_cndmask_b32_e64 v31, v78, v96, s[8:9]
	v_cndmask_b32_e64 v30, v76, v94, s[8:9]
	v_pk_fma_f32 v[32:33], v[58:59], v[32:33], v[70:71]
	s_nop 0
	v_pk_fma_f32 v[30:31], v[62:63], v[30:31], v[32:33]
	s_nop 0
	v_pk_fma_f32 v[30:31], v[110:111], v[66:67], v[30:31]
	v_mov_b32_dpp v80, v112 row_ror:1 row_mask:0xf bank_mask:0xf
	v_mul_f32_e32 v28, 0xbfb8aa3b, v30
	v_exp_f32_e32 v32, v28
	v_mul_f32_e32 v28, 0xbfb8aa3b, v31
	v_exp_f32_e32 v33, v28
	v_cndmask_b32_e64 v28, v80, v85, s[8:9]
	v_mov_b32_dpp v81, v112 row_ror:2 row_mask:0xf bank_mask:0xf
	v_pk_add_f32 v[32:33], v[32:33], 1.0 op_sel_hi:[1,0]
	v_mov_b32_dpp v83, v113 row_ror:2 row_mask:0xf bank_mask:0xf
	v_mov_b32_dpp v82, v113 row_ror:1 row_mask:0xf bank_mask:0xf
	v_cndmask_b32_e64 v75, v98, v83, s[10:11]
	v_cndmask_b32_e64 v74, v87, v81, s[10:11]
	v_cndmask_b32_e64 v29, v82, v99, s[8:9]
	v_pk_fma_f32 v[74:75], v[60:61], v[74:75], v[72:73]
	ds_read2_b32 v[26:27], v214 offset0:144 offset1:160
	v_pk_fma_f32 v[28:29], v[64:65], v[28:29], v[74:75]
	v_rcp_f32_e32 v33, v33
	v_pk_fma_f32 v[28:29], v[112:113], v[68:69], v[28:29]
	s_nop 0
	v_mul_f32_e32 v74, 0xbfb8aa3b, v28
	v_mul_f32_e32 v75, 0xbfb8aa3b, v29
	v_exp_f32_e32 v74, v74
	v_exp_f32_e32 v75, v75
	v_rcp_f32_e32 v32, v32
	s_nop 0
	v_pk_mul_f32 v[30:31], v[30:31], v[32:33]
	v_pk_add_f32 v[74:75], v[74:75], 1.0 op_sel_hi:[1,0]
	s_waitcnt lgkmcnt(0)
	v_pk_mul_f32 v[22:23], v[22:23], v[26:27] op_sel_hi:[1,0]
	s_nop 0
	v_pk_mul_f32 v[22:23], v[22:23], v[30:31]
	v_rcp_f32_e32 v31, v75
	v_mov_b32_dpp v85, v106 row_ror:2 row_mask:0xf bank_mask:0xf
	v_mov_b32_dpp v94, v107 row_ror:2 row_mask:0xf bank_mask:0xf
	v_rcp_f32_e32 v30, v74
	v_mov_b32_dpp v84, v106 row_ror:1 row_mask:0xf bank_mask:0xf
	v_mov_b32_dpp v87, v107 row_ror:1 row_mask:0xf bank_mask:0xf
	v_cndmask_b32_e64 v33, v91, v94, s[10:11]
	v_cndmask_b32_e64 v32, v89, v85, s[10:11]
	v_pk_mul_f32 v[28:29], v[28:29], v[30:31]
	v_cndmask_b32_e64 v31, v87, v90, s[8:9]
	v_cndmask_b32_e64 v30, v84, v88, s[8:9]
	v_pk_fma_f32 v[32:33], v[42:43], v[32:33], v[54:55]
	v_pk_mul_f32 v[24:25], v[24:25], v[26:27] op_sel_hi:[1,0]
	v_pk_fma_f32 v[30:31], v[46:47], v[30:31], v[32:33]
	v_pk_mul_f32 v[24:25], v[24:25], v[28:29]
	v_pk_fma_f32 v[30:31], v[106:107], v[50:51], v[30:31]
	s_nop 0
	v_mul_f32_e32 v28, 0xbfb8aa3b, v30
	v_exp_f32_e32 v32, v28
	v_mul_f32_e32 v28, 0xbfb8aa3b, v31
	v_exp_f32_e32 v33, v28
	v_mov_b32_dpp v96, v108 row_ror:2 row_mask:0xf bank_mask:0xf
	v_pk_add_f32 v[32:33], v[32:33], 1.0 op_sel_hi:[1,0]
	v_mov_b32_dpp v98, v109 row_ror:2 row_mask:0xf bank_mask:0xf
	v_mov_b32_dpp v95, v108 row_ror:1 row_mask:0xf bank_mask:0xf
	v_mov_b32_dpp v97, v109 row_ror:1 row_mask:0xf bank_mask:0xf
	v_cndmask_b32_e64 v75, v101, v98, s[10:11]
	v_cndmask_b32_e64 v74, v93, v96, s[10:11]
	v_cndmask_b32_e64 v29, v97, v100, s[8:9]
	v_cndmask_b32_e64 v28, v95, v92, s[8:9]
	v_pk_fma_f32 v[74:75], v[44:45], v[74:75], v[56:57]
	v_pk_mul_f32 v[18:19], v[18:19], v[26:27] op_sel_hi:[1,0]
	v_pk_fma_f32 v[28:29], v[48:49], v[28:29], v[74:75]
	v_rcp_f32_e32 v33, v33
	v_pk_fma_f32 v[28:29], v[108:109], v[52:53], v[28:29]
	s_nop 0
	v_mul_f32_e32 v74, 0xbfb8aa3b, v28
	v_mul_f32_e32 v75, 0xbfb8aa3b, v29
	v_exp_f32_e32 v74, v74
	v_exp_f32_e32 v75, v75
	v_rcp_f32_e32 v32, v32
	s_nop 0
	v_pk_mul_f32 v[30:31], v[30:31], v[32:33]
; #define LAS __attribute__((address_space(3)))
; __device__ __forceinline__ size_t hidx(size_t r, int c) { return ((size_t)(c >> 6) * MTOT + r) * 64 + (c & 63); }
; __device__ __forceinline__ u32x4 pack8(const f32x4 a, const f32x4 b) { u32x4 w; w.x = cvt_pk_bf16(a[0], a[1]); w.y = cvt_pk_bf16(a[2], a[3]); w.z = cvt_pk_bf16(b[0], b[1]); w.w = cvt_pk_bf16(b[2], b[3]); return w; }
; __device__ __forceinline__ float sigm(float x) { return 1.f / (1.f + __builtin_amdgcn_exp2f(-LOG2E * x)); }
; __device__ __forceinline__ int halo_idx(int slot, int wc, int row, int ci) { return ((slot * 4 + wc) * 2 + row) * 32 + ci; }
;     __device__ __forceinline__ void operator()(const f32x4 (&acc)[2][2][4][2], const Unit& u, int wr, int wc, int fr, int fq) const {
;     ...
;             for (int m = 0; m < 4; ++m) { const int r = row0 + 128 * ai + 16 * m; const float rs = rsl[128 * ai + 64 * wr + 16 * m + fr]; f32x4 o[2];
; _Pragma("unroll")
;                 for (int n = 0; n < 2; ++n) { f32x4 p1, p2, q1, q2;
;                     if (m > 0) {
; _Pragma("unroll")
;                         for (int j = 0; j < 4; ++j) { q1[j] = row_from_below<1>(gs[ai][m - 1][n][j]); q2[j] = row_from_below<2>(gs[ai][m - 1][n][j]); } }
;                     else { const int slot = (2 * ai + wr) ? (2 * ai + wr) : 4 + (u.pm & 1);
;                         q1 = *(const LAS f32x4*)(hal + halo_idx(slot, wc, 1, ci0 + 4 * n)); q2 = *(const LAS f32x4*)(hal + halo_idx(slot, wc, fr == 0 ? 0 : 1, ci0 + 4 * n)); }
; _Pragma("unroll")
;                     for (int j = 0; j < 4; ++j) { p1[j] = row_from_below<1>(gs[ai][m][n][j]); p2[j] = row_from_below<2>(gs[ai][m][n][j]); }
;                     const f32x4 h1 = fr >= 1 ? p1 : q1, h0 = fr >= 2 ? p2 : q2;
;                     const f32x4 cv = bb[n] + w0[n] * h0 + w1[n] * h1 + w2[n] * gs[ai][m][n];
; _Pragma("unroll")
;                     for (int j = 0; j < 4; ++j) o[n][j] = cv[j] * sigm(cv[j]) * (acc[ai][1][m][n][j] * rs); }
;                 *(u32x4*)(H + hidx(r, ch0)) = pack8(o[0], o[1]); }
	v_pk_add_f32 v[74:75], v[74:75], 1.0 op_sel_hi:[1,0]
	v_pk_mul_f32 v[30:31], v[18:19], v[30:31]
	v_pk_mul_f32 v[20:21], v[20:21], v[26:27] op_sel_hi:[1,0]
	v_pk_mul_f32 v[6:7], v[6:7], v[86:87] op_sel_hi:[1,0]
	v_pk_mul_f32 v[8:9], v[8:9], v[86:87] op_sel_hi:[1,0]
	v_rcp_f32_e32 v19, v75
	v_rcp_f32_e32 v18, v74
	v_add_u32_e32 v32, 0x90, v122
	v_pk_mul_f32 v[18:19], v[28:29], v[18:19]
	v_ashrrev_i32_e32 v33, 31, v32
	v_pk_mul_f32 v[28:29], v[20:21], v[18:19]
	v_cvt_pk_bf16_f32 v18, v22, v23
	v_lshl_add_u64 v[22:23], s[48:49], 0, v[32:33]
	v_cvt_pk_bf16_f32 v20, v30, v31
	v_cvt_pk_bf16_f32 v21, v28, v29
	v_lshlrev_b64 v[22:23], 7, v[22:23]
	v_cvt_pk_bf16_f32 v19, v24, v25
	v_lshl_add_u64 v[22:23], v[156:157], 0, v[22:23]
	v_mov_b32_dpp v29, v172 row_ror:2 row_mask:0xf bank_mask:0xf
	v_mov_b32_dpp v31, v173 row_ror:2 row_mask:0xf bank_mask:0xf
	global_store_dwordx4 v[22:23], v[18:21], off
	v_mov_b32_dpp v28, v172 row_ror:1 row_mask:0xf bank_mask:0xf
	v_mov_b32_dpp v30, v173 row_ror:1 row_mask:0xf bank_mask:0xf
	v_cndmask_b32_e64 v23, v79, v31, s[10:11]
	v_cndmask_b32_e64 v22, v77, v29, s[10:11]
	v_cndmask_b32_e64 v21, v30, v78, s[8:9]
	v_cndmask_b32_e64 v20, v28, v76, s[8:9]
	v_pk_fma_f32 v[22:23], v[58:59], v[22:23], v[70:71]
	s_nop 0
	v_pk_fma_f32 v[20:21], v[62:63], v[20:21], v[22:23]
	s_nop 0
	v_pk_fma_f32 v[20:21], v[172:173], v[66:67], v[20:21]
	s_nop 0
	v_mul_f32_e32 v18, 0xbfb8aa3b, v20
	v_exp_f32_e32 v22, v18
	v_mul_f32_e32 v18, 0xbfb8aa3b, v21
	v_exp_f32_e32 v23, v18
	v_mov_b32_dpp v33, v170 row_ror:2 row_mask:0xf bank_mask:0xf
	v_mov_b32_dpp v75, v171 row_ror:2 row_mask:0xf bank_mask:0xf
	v_pk_add_f32 v[22:23], v[22:23], 1.0 op_sel_hi:[1,0]
	v_mov_b32_dpp v32, v170 row_ror:1 row_mask:0xf bank_mask:0xf
	v_mov_b32_dpp v74, v171 row_ror:1 row_mask:0xf bank_mask:0xf
	v_cndmask_b32_e64 v25, v83, v75, s[10:11]
	v_cndmask_b32_e64 v24, v81, v33, s[10:11]
	v_cndmask_b32_e64 v19, v74, v82, s[8:9]
	v_cndmask_b32_e64 v18, v32, v80, s[8:9]
	v_pk_fma_f32 v[24:25], v[60:61], v[24:25], v[72:73]
	s_nop 0
	v_pk_fma_f32 v[18:19], v[64:65], v[18:19], v[24:25]
	v_rcp_f32_e32 v23, v23
	v_pk_fma_f32 v[18:19], v[170:171], v[68:69], v[18:19]
	s_nop 0
	v_mul_f32_e32 v24, 0xbfb8aa3b, v18
	v_mul_f32_e32 v25, 0xbfb8aa3b, v19
	v_exp_f32_e32 v24, v24
	v_exp_f32_e32 v25, v25
	v_rcp_f32_e32 v22, v22
	s_nop 0
	v_pk_mul_f32 v[20:21], v[20:21], v[22:23]
	v_pk_add_f32 v[22:23], v[24:25], 1.0 op_sel_hi:[1,0]
	v_mov_b32_e32 v24, v27
	v_pk_mul_f32 v[14:15], v[14:15], v[24:25] op_sel_hi:[1,0]
	s_nop 0
	v_pk_mul_f32 v[14:15], v[14:15], v[20:21]
	v_rcp_f32_e32 v21, v23
	v_pk_mul_f32 v[16:17], v[16:17], v[24:25] op_sel_hi:[1,0]
	v_mov_b32_dpp v76, v168 row_ror:2 row_mask:0xf bank_mask:0xf
	v_mov_b32_dpp v78, v169 row_ror:2 row_mask:0xf bank_mask:0xf
	v_rcp_f32_e32 v20, v22
	v_mov_b32_dpp v25, v168 row_ror:1 row_mask:0xf bank_mask:0xf
	v_mov_b32_dpp v77, v169 row_ror:1 row_mask:0xf bank_mask:0xf
	v_cndmask_b32_e64 v23, v94, v78, s[10:11]
	v_cndmask_b32_e64 v22, v85, v76, s[10:11]
	v_pk_mul_f32 v[18:19], v[18:19], v[20:21]
	v_cndmask_b32_e64 v21, v77, v87, s[8:9]
	v_cndmask_b32_e64 v20, v25, v84, s[8:9]
	v_pk_fma_f32 v[22:23], v[42:43], v[22:23], v[54:55]
	v_pk_mul_f32 v[16:17], v[16:17], v[18:19]
	v_pk_fma_f32 v[20:21], v[46:47], v[20:21], v[22:23]
	s_nop 0
	v_pk_fma_f32 v[20:21], v[168:169], v[50:51], v[20:21]
	s_nop 0
	v_mul_f32_e32 v18, 0xbfb8aa3b, v20
	v_exp_f32_e32 v22, v18
	v_mul_f32_e32 v18, 0xbfb8aa3b, v21
	v_exp_f32_e32 v23, v18
	v_mov_b32_dpp v80, v166 row_ror:2 row_mask:0xf bank_mask:0xf
	v_pk_add_f32 v[22:23], v[22:23], 1.0 op_sel_hi:[1,0]
	v_mov_b32_dpp v82, v167 row_ror:2 row_mask:0xf bank_mask:0xf
	v_mov_b32_dpp v79, v166 row_ror:1 row_mask:0xf bank_mask:0xf
	v_mov_b32_dpp v81, v167 row_ror:1 row_mask:0xf bank_mask:0xf
	v_cndmask_b32_e64 v27, v98, v82, s[10:11]
	v_cndmask_b32_e64 v26, v96, v80, s[10:11]
	v_cndmask_b32_e64 v19, v81, v97, s[8:9]
	v_cndmask_b32_e64 v18, v79, v95, s[8:9]
	v_pk_fma_f32 v[26:27], v[44:45], v[26:27], v[56:57]
	v_pk_mul_f32 v[10:11], v[10:11], v[24:25] op_sel_hi:[1,0]
	v_pk_fma_f32 v[18:19], v[48:49], v[18:19], v[26:27]
	v_rcp_f32_e32 v23, v23
	v_pk_fma_f32 v[18:19], v[166:167], v[52:53], v[18:19]
	s_nop 0
	v_mul_f32_e32 v26, 0xbfb8aa3b, v18
	v_mul_f32_e32 v27, 0xbfb8aa3b, v19
	v_exp_f32_e32 v26, v26
	v_exp_f32_e32 v27, v27
	v_rcp_f32_e32 v22, v22
	s_nop 0
	v_pk_mul_f32 v[20:21], v[20:21], v[22:23]
	v_pk_add_f32 v[26:27], v[26:27], 1.0 op_sel_hi:[1,0]
	v_pk_mul_f32 v[20:21], v[10:11], v[20:21]
	v_pk_mul_f32 v[12:13], v[12:13], v[24:25] op_sel_hi:[1,0]
	v_pk_mul_f32 v[2:3], v[2:3], v[86:87] op_sel_hi:[1,0]
	v_pk_mul_f32 v[4:5], v[4:5], v[86:87] op_sel_hi:[1,0]
	v_div_scale_f32 v22, s[0:1], v26, v26, 1.0
	v_rcp_f32_e32 v23, v22
	v_rcp_f32_e32 v11, v27
	v_fma_f32 v10, -v22, v23, 1.0
	v_fmac_f32_e32 v23, v10, v23
	v_div_scale_f32 v10, vcc, 1.0, v26, 1.0
	v_mul_f32_e32 v27, v10, v23
	v_fma_f32 v83, -v22, v27, v10
	v_fmac_f32_e32 v27, v83, v23
	v_fma_f32 v10, -v22, v27, v10
	v_div_fmas_f32 v10, v10, v23, v27
	v_div_fixup_f32 v10, v10, v26, 1.0
	v_add_u32_e32 v22, 0xa0, v122
	v_pk_mul_f32 v[10:11], v[18:19], v[10:11]
	v_ashrrev_i32_e32 v23, 31, v22
	v_pk_mul_f32 v[18:19], v[12:13], v[10:11]
	v_cvt_pk_bf16_f32 v10, v14, v15
	v_lshl_add_u64 v[14:15], s[48:49], 0, v[22:23]
	v_lshlrev_b64 v[14:15], 7, v[14:15]
; #define PG8_BAR __builtin_amdgcn_s_barrier()
; #define LAS __attribute__((address_space(3)))
; __device__ __forceinline__ size_t hidx(size_t r, int c) { return ((size_t)(c >> 6) * MTOT + r) * 64 + (c & 63); }
; template <class Epi, class Sched, bool ALIGN_EPI = false, bool SP2 = false>
; __device__ __forceinline__ void gemm_phase(PG8_LAS unsigned char* lds, const Gemm g, const Sched& S, const Epi& E) {
;     ...
;         if constexpr (!Epi::AFTER_DRAIN) { E(acc, cur, wr, wc, fr, fq); S.done(cur); }
;         if (!has_next) break;
; #pragma unroll
;         for (int a = 0; a < 2; ++a)
; #pragma unroll
;             for (int b = 0; b < 2; ++b)
; #pragma unroll
;                 for (int m = 0; m < 4; ++m)
; #pragma unroll
;                     for (int n = 0; n < 2; ++n) acc[a][b][m][n] = (f32x4){0.f, 0.f, 0.f, 0.f};
;         cur = nxt; cA = nA; cB = nB; ++ui;
;         if constexpr (ALIGN_EPI) { if (wr == 1) PG8_BAR; }
;     __device__ __forceinline__ void operator()(const f32x4 (&acc)[2][2][4][2], const Unit& u, int wr, int wc, int fr, int fq) const {
;     ...
;             for (int m = 0; m < 4; ++m) { const int r = row0 + 128 * ai + 16 * m; const float rs = rsl[128 * ai + 64 * wr + 16 * m + fr]; f32x4 o[2];
; _Pragma("unroll")
;                 for (int n = 0; n < 2; ++n) { f32x4 p1, p2, q1, q2;
;                     if (m > 0) {
; _Pragma("unroll")
;                         for (int j = 0; j < 4; ++j) { q1[j] = row_from_below<1>(gs[ai][m - 1][n][j]); q2[j] = row_from_below<2>(gs[ai][m - 1][n][j]); } }
;                     else { const int slot = (2 * ai + wr) ? (2 * ai + wr) : 4 + (u.pm & 1);
;                         q1 = *(const LAS f32x4*)(hal + halo_idx(slot, wc, 1, ci0 + 4 * n)); q2 = *(const LAS f32x4*)(hal + halo_idx(slot, wc, fr == 0 ? 0 : 1, ci0 + 4 * n)); }
; _Pragma("unroll")
;                     for (int j = 0; j < 4; ++j) { p1[j] = row_from_below<1>(gs[ai][m][n][j]); p2[j] = row_from_below<2>(gs[ai][m][n][j]); }
;                     const f32x4 h1 = fr >= 1 ? p1 : q1, h0 = fr >= 2 ? p2 : q2;
;                     const f32x4 cv = bb[n] + w0[n] * h0 + w1[n] * h1 + w2[n] * gs[ai][m][n];
; _Pragma("unroll")
;                     for (int j = 0; j < 4; ++j) o[n][j] = cv[j] * sigm(cv[j]) * (acc[ai][1][m][n][j] * rs); }
;                 *(u32x4*)(H + hidx(r, ch0)) = pack8(o[0], o[1]); }
	v_cvt_pk_bf16_f32 v11, v16, v17
	v_cvt_pk_bf16_f32 v12, v20, v21
	v_cvt_pk_bf16_f32 v13, v18, v19
	v_lshl_add_u64 v[14:15], v[156:157], 0, v[14:15]
	global_store_dwordx4 v[14:15], v[10:13], off
	s_nop 0
	v_mov_b32_dpp v14, v38 row_ror:2 row_mask:0xf bank_mask:0xf
	v_mov_b32_dpp v15, v39 row_ror:2 row_mask:0xf bank_mask:0xf
	v_mov_b32_dpp v10, v38 row_ror:1 row_mask:0xf bank_mask:0xf
	v_mov_b32_dpp v12, v39 row_ror:1 row_mask:0xf bank_mask:0xf
	v_cndmask_b32_e64 v15, v31, v15, s[10:11]
	v_cndmask_b32_e64 v14, v29, v14, s[10:11]
	v_cndmask_b32_e64 v13, v12, v30, s[8:9]
	v_cndmask_b32_e64 v12, v10, v28, s[8:9]
	v_pk_fma_f32 v[14:15], v[58:59], v[14:15], v[70:71]
	s_nop 0
	v_pk_fma_f32 v[12:13], v[62:63], v[12:13], v[14:15]
	s_nop 0
	v_pk_fma_f32 v[12:13], v[38:39], v[66:67], v[12:13]
	v_mov_b32_dpp v16, v40 row_ror:1 row_mask:0xf bank_mask:0xf
	v_mul_f32_e32 v10, 0xbfb8aa3b, v12
	v_exp_f32_e32 v14, v10
	v_mul_f32_e32 v10, 0xbfb8aa3b, v13
	v_exp_f32_e32 v15, v10
	v_mov_b32_dpp v18, v40 row_ror:2 row_mask:0xf bank_mask:0xf
	v_cndmask_b32_e64 v10, v16, v32, s[8:9]
	v_cndmask_b32_e64 v16, v33, v18, s[10:11]
	v_pk_add_f32 v[14:15], v[14:15], 1.0 op_sel_hi:[1,0]
	v_mov_b32_dpp v17, v41 row_ror:2 row_mask:0xf bank_mask:0xf
	v_cndmask_b32_e64 v17, v75, v17, s[10:11]
	v_mov_b32_dpp v11, v41 row_ror:1 row_mask:0xf bank_mask:0xf
	v_cndmask_b32_e64 v11, v11, v74, s[8:9]
	v_pk_fma_f32 v[16:17], v[60:61], v[16:17], v[72:73]
	s_nop 0
	v_pk_fma_f32 v[10:11], v[64:65], v[10:11], v[16:17]
	v_rcp_f32_e32 v15, v15
	v_pk_fma_f32 v[10:11], v[40:41], v[68:69], v[10:11]
	s_nop 0
	v_mul_f32_e32 v16, 0xbfb8aa3b, v10
	v_mul_f32_e32 v17, 0xbfb8aa3b, v11
	v_exp_f32_e32 v16, v16
	v_exp_f32_e32 v17, v17
	v_rcp_f32_e32 v14, v14
	s_nop 0
	v_pk_mul_f32 v[12:13], v[12:13], v[14:15]
	v_pk_add_f32 v[16:17], v[16:17], 1.0 op_sel_hi:[1,0]
	v_pk_mul_f32 v[6:7], v[6:7], v[12:13]
	s_nop 0
	v_rcp_f32_e32 v13, v17
	v_rcp_f32_e32 v12, v16
	s_nop 0
	v_pk_mul_f32 v[10:11], v[10:11], v[12:13]
	s_nop 0
	v_pk_mul_f32 v[8:9], v[8:9], v[10:11]
	v_mov_b32_dpp v14, v34 row_ror:2 row_mask:0xf bank_mask:0xf
	v_mov_b32_dpp v15, v35 row_ror:2 row_mask:0xf bank_mask:0xf
	v_mov_b32_dpp v10, v34 row_ror:1 row_mask:0xf bank_mask:0xf
	v_mov_b32_dpp v12, v35 row_ror:1 row_mask:0xf bank_mask:0xf
	v_cndmask_b32_e64 v15, v78, v15, s[10:11]
	v_cndmask_b32_e64 v14, v76, v14, s[10:11]
	v_cndmask_b32_e64 v13, v12, v77, s[8:9]
	v_cndmask_b32_e64 v12, v10, v25, s[8:9]
	v_pk_fma_f32 v[14:15], v[42:43], v[14:15], v[54:55]
	s_nop 0
	v_pk_fma_f32 v[12:13], v[46:47], v[12:13], v[14:15]
	s_nop 0
	v_pk_fma_f32 v[12:13], v[34:35], v[50:51], v[12:13]
	v_mov_b32_dpp v16, v36 row_ror:1 row_mask:0xf bank_mask:0xf
	v_mul_f32_e32 v10, 0xbfb8aa3b, v12
	v_exp_f32_e32 v14, v10
	v_mul_f32_e32 v10, 0xbfb8aa3b, v13
	v_exp_f32_e32 v15, v10
	v_mov_b32_dpp v18, v36 row_ror:2 row_mask:0xf bank_mask:0xf
	v_cndmask_b32_e64 v10, v16, v79, s[8:9]
	v_cndmask_b32_e64 v16, v80, v18, s[10:11]
	v_pk_add_f32 v[14:15], v[14:15], 1.0 op_sel_hi:[1,0]
	v_mov_b32_dpp v17, v37 row_ror:2 row_mask:0xf bank_mask:0xf
	v_cndmask_b32_e64 v17, v82, v17, s[10:11]
	v_mov_b32_dpp v11, v37 row_ror:1 row_mask:0xf bank_mask:0xf
	v_cndmask_b32_e64 v11, v11, v81, s[8:9]
	v_pk_fma_f32 v[16:17], v[44:45], v[16:17], v[56:57]
	s_nop 0
	v_pk_fma_f32 v[10:11], v[48:49], v[10:11], v[16:17]
	v_div_scale_f32 v18, s[0:1], v14, v14, 1.0
	v_rcp_f32_e32 v20, v18
	v_rcp_f32_e32 v15, v15
	v_pk_fma_f32 v[10:11], v[36:37], v[52:53], v[10:11]
	v_fma_f32 v16, -v18, v20, 1.0
	v_fmac_f32_e32 v20, v16, v20
	v_div_scale_f32 v16, vcc, 1.0, v14, 1.0
	v_mul_f32_e32 v19, v16, v20
	v_fma_f32 v17, -v18, v19, v16
	v_fmac_f32_e32 v19, v17, v20
	v_fma_f32 v18, -v18, v19, v16
	v_mul_f32_e32 v16, 0xbfb8aa3b, v10
	v_mul_f32_e32 v17, 0xbfb8aa3b, v11
	v_exp_f32_e32 v16, v16
	v_exp_f32_e32 v17, v17
	v_div_fmas_f32 v18, v18, v20, v19
	v_div_fixup_f32 v14, v18, v14, 1.0
	v_pk_mul_f32 v[12:13], v[12:13], v[14:15]
	v_pk_add_f32 v[16:17], v[16:17], 1.0 op_sel_hi:[1,0]
	v_pk_mul_f32 v[12:13], v[2:3], v[12:13]
	v_div_scale_f32 v18, s[0:1], v17, v17, 1.0
	v_rcp_f32_e32 v19, v18
	s_nop 0
	v_fma_f32 v2, -v18, v19, 1.0
	v_fmac_f32_e32 v19, v2, v19
	v_div_scale_f32 v2, vcc, 1.0, v17, 1.0
	v_mul_f32_e32 v3, v2, v19
	v_fma_f32 v14, -v18, v3, v2
	v_fmac_f32_e32 v3, v14, v19
	v_div_scale_f32 v14, s[0:1], v16, v16, 1.0
	v_rcp_f32_e32 v15, v14
	v_fma_f32 v2, -v18, v3, v2
	v_div_fmas_f32 v2, v2, v19, v3
	v_div_fixup_f32 v3, v2, v17, 1.0
	v_fma_f32 v2, -v14, v15, 1.0
	v_fmac_f32_e32 v15, v2, v15
	v_div_scale_f32 v2, vcc, 1.0, v16, 1.0
	v_mul_f32_e32 v17, v2, v15
	v_fma_f32 v18, -v14, v17, v2
	v_fmac_f32_e32 v17, v18, v15
	v_fma_f32 v2, -v14, v17, v2
	v_div_fmas_f32 v2, v2, v15, v17
	v_div_fixup_f32 v2, v2, v16, 1.0
	v_add_u32_e32 v14, 0xb0, v122
	v_pk_mul_f32 v[2:3], v[10:11], v[2:3]
	v_ashrrev_i32_e32 v15, 31, v14
	v_pk_mul_f32 v[10:11], v[4:5], v[2:3]
	v_cvt_pk_bf16_f32 v2, v6, v7
	v_lshl_add_u64 v[6:7], s[48:49], 0, v[14:15]
	v_lshlrev_b64 v[6:7], 7, v[6:7]
	v_cvt_pk_bf16_f32 v3, v8, v9
	v_cvt_pk_bf16_f32 v4, v12, v13
	v_cvt_pk_bf16_f32 v5, v10, v11
	v_lshl_add_u64 v[6:7], v[156:157], 0, v[6:7]
	s_mov_b64 s[0:1], -1
	global_store_dwordx4 v[6:7], v[2:5], off
	s_cbranch_scc1 .LBB0_1073
	s_andn2_b64 vcc, exec, s[42:43]
	s_cbranch_vccnz .LBB0_1072
	s_barrier
	s_branch .LBB0_1072
